# GEMM K-loops: register double-buffered LDS fragments, DMA interleaved with MFMA, per-WG K rotation
# speedup vs baseline: 1.0321x; 1.0321x over previous
.LBB0_71:
	s_ashr_i32 s36, s31, 2
	s_and_b32 s36, s36, -8
	s_or_b32 s36, s36, s3
	s_ashr_i32 s37, s36, 31
	s_lshr_b32 s37, s37, 29
	s_add_i32 s37, s36, s37
	s_ashr_i32 s43, s37, 3
	s_and_b32 s37, s37, 0x1ffff8
	s_bfe_u32 s5, s31, 0x20003
	s_sub_i32 s42, s36, s37
	s_lshl_b32 s37, s43, 2
	s_lshl_b32 s33, s5, 8
	s_or_b32 s37, s37, s5
	s_lshl_b32 s5, s42, 11
	s_lshl_b32 s42, s31, 8
	s_and_b32 s42, s42, 0x700
	s_or_b32 s42, s5, s42
	v_add_u32_e32 v0, s42, v187
	v_ashrrev_i32_e32 v1, 31, v0
	v_lshl_add_u32 v2, s37, 8, v187
	v_lshlrev_b64 v[0:1], 12, v[0:1]
	v_ashrrev_i32_e32 v3, 31, v2
	v_readfirstlane_b32 s5, v188
	v_lshl_add_u64 v[0:1], v[146:147], 0, v[0:1]
	v_lshlrev_b64 v[2:3], 12, v[2:3]
	s_mov_b32 m0, s5
	v_readfirstlane_b32 s5, v200
	v_lshl_add_u64 v[2:3], v[148:149], 0, v[2:3]
	global_load_lds_dwordx4 v[0:1], off
	s_mov_b32 m0, s5
	v_readfirstlane_b32 s5, v201
	global_load_lds_dwordx4 v[2:3], off
	v_lshl_add_u64 v[4:5], v[0:1], 0, s[6:7]
	s_mov_b32 m0, s5
	v_readfirstlane_b32 s5, v202
	global_load_lds_dwordx4 v[4:5], off
	v_lshl_add_u64 v[4:5], v[2:3], 0, s[6:7]
	s_mov_b32 m0, s5
	v_readfirstlane_b32 s5, v203
	global_load_lds_dwordx4 v[4:5], off
	v_lshl_add_u64 v[4:5], v[0:1], 0, s[14:15]
	s_mov_b32 m0, s5
	v_readfirstlane_b32 s5, v204
	global_load_lds_dwordx4 v[4:5], off
	v_lshl_add_u64 v[4:5], v[2:3], 0, s[14:15]
	s_mov_b32 m0, s5
	v_readfirstlane_b32 s5, v205
	global_load_lds_dwordx4 v[4:5], off
	v_lshl_add_u64 v[0:1], v[0:1], 0, s[20:21]
	s_mov_b32 m0, s5
	v_readfirstlane_b32 s5, v206
	global_load_lds_dwordx4 v[0:1], off
	v_lshl_add_u64 v[0:1], v[2:3], 0, s[20:21]
	s_mov_b32 m0, s5
	s_and_b32 s4, s35, 0x700
	global_load_lds_dwordx4 v[0:1], off
	s_lshl_b32 s5, s36, 11
	s_or_b32 s4, s4, s5
	v_add_u32_e32 v0, s4, v187
	s_lshl_b32 s4, s43, 14
	v_subrev_u32_e32 v0, s4, v0
	v_ashrrev_i32_e32 v1, 31, v0
	s_lshl_b32 s4, s43, 10
	v_lshlrev_b64 v[0:1], 12, v[0:1]
	s_or_b32 s4, s33, s4
	v_lshl_add_u64 v[128:129], v[158:159], 0, v[0:1]
	v_add_u32_e32 v0, s4, v187
	v_ashrrev_i32_e32 v1, 31, v0
	v_lshlrev_b64 v[0:1], 12, v[0:1]
	v_lshl_add_u64 v[130:131], v[160:161], 0, v[0:1]
	s_mov_b64 s[4:5], 0
	s_mov_b32 s43, 0
	v_mov_b32_e32 v0, 0
	v_mov_b32_e32 v1, v145
	v_mov_b32_e32 v2, v145
	v_mov_b32_e32 v3, v145
	v_mov_b32_e32 v4, v145
	v_mov_b32_e32 v5, v145
	v_mov_b32_e32 v6, v145
	v_mov_b32_e32 v7, v145
	s_waitcnt vmcnt(0)
	v_mov_b32_e32 v8, v145
	v_mov_b32_e32 v9, v145
	v_mov_b32_e32 v10, v145
	v_mov_b32_e32 v11, v145
	v_mov_b32_e32 v12, v145
	v_mov_b32_e32 v13, v145
	v_mov_b32_e32 v14, v145
	v_mov_b32_e32 v15, v145
	v_mov_b32_e32 v16, 0
	v_mov_b32_e32 v17, v145
	v_mov_b32_e32 v18, v145
	v_mov_b32_e32 v19, v145
	v_mov_b32_e32 v20, v145
	v_mov_b32_e32 v21, v145
	v_mov_b32_e32 v22, v145
	v_mov_b32_e32 v23, v145
	v_mov_b32_e32 v24, v145
	v_mov_b32_e32 v25, v145
	v_mov_b32_e32 v26, v145
	v_mov_b32_e32 v27, v145
	v_mov_b32_e32 v28, v145
	v_mov_b32_e32 v29, v145
	v_mov_b32_e32 v30, v145
	v_mov_b32_e32 v31, v145
	v_mov_b32_e32 v32, 0
	v_mov_b32_e32 v33, v145
	v_mov_b32_e32 v34, v145
	v_mov_b32_e32 v35, v145
	v_mov_b32_e32 v36, v145
	v_mov_b32_e32 v37, v145
	v_mov_b32_e32 v38, v145
	v_mov_b32_e32 v39, v145
	v_mov_b32_e32 v40, v145
	v_mov_b32_e32 v41, v145
	v_mov_b32_e32 v42, v145
	v_mov_b32_e32 v43, v145
	v_mov_b32_e32 v44, v145
	v_mov_b32_e32 v45, v145
	v_mov_b32_e32 v46, v145
	v_mov_b32_e32 v47, v145
	v_mov_b32_e32 v48, 0
	v_mov_b32_e32 v49, v145
	v_mov_b32_e32 v50, v145
	v_mov_b32_e32 v51, v145
	v_mov_b32_e32 v52, v145
	v_mov_b32_e32 v53, v145
	v_mov_b32_e32 v54, v145
	v_mov_b32_e32 v55, v145
	v_mov_b32_e32 v56, v145
	v_mov_b32_e32 v57, v145
	v_mov_b32_e32 v58, v145
	v_mov_b32_e32 v59, v145
	v_mov_b32_e32 v60, v145
	v_mov_b32_e32 v61, v145
	v_mov_b32_e32 v62, v145
	v_mov_b32_e32 v63, v145
	v_mov_b32_e32 v64, 0
	v_mov_b32_e32 v65, v145
	v_mov_b32_e32 v66, v145
	v_mov_b32_e32 v67, v145
	v_mov_b32_e32 v68, v145
	v_mov_b32_e32 v69, v145
	v_mov_b32_e32 v70, v145
	v_mov_b32_e32 v71, v145
	v_mov_b32_e32 v72, v145
	v_mov_b32_e32 v73, v145
	v_mov_b32_e32 v74, v145
	v_mov_b32_e32 v75, v145
	v_mov_b32_e32 v76, v145
	v_mov_b32_e32 v77, v145
	v_mov_b32_e32 v78, v145
	v_mov_b32_e32 v79, v145
	v_mov_b32_e32 v80, 0
	v_mov_b32_e32 v81, v145
	v_mov_b32_e32 v82, v145
	v_mov_b32_e32 v83, v145
	v_mov_b32_e32 v84, v145
	v_mov_b32_e32 v85, v145
	v_mov_b32_e32 v86, v145
	v_mov_b32_e32 v87, v145
	v_mov_b32_e32 v88, v145
	v_mov_b32_e32 v89, v145
	v_mov_b32_e32 v90, v145
	v_mov_b32_e32 v91, v145
	v_mov_b32_e32 v92, v145
	v_mov_b32_e32 v93, v145
	v_mov_b32_e32 v94, v145
	v_mov_b32_e32 v95, v145
	v_mov_b32_e32 v96, 0
	v_mov_b32_e32 v97, v145
	v_mov_b32_e32 v98, v145
	v_mov_b32_e32 v99, v145
	v_mov_b32_e32 v100, v145
	v_mov_b32_e32 v101, v145
	v_mov_b32_e32 v102, v145
	v_mov_b32_e32 v103, v145
	v_mov_b32_e32 v104, v145
	v_mov_b32_e32 v105, v145
	v_mov_b32_e32 v106, v145
	v_mov_b32_e32 v107, v145
	v_mov_b32_e32 v108, v145
	v_mov_b32_e32 v109, v145
	v_mov_b32_e32 v110, v145
	v_mov_b32_e32 v111, v145
	v_mov_b32_e32 v112, 0
	v_mov_b32_e32 v113, v145
	v_mov_b32_e32 v114, v145
	v_mov_b32_e32 v115, v145
	v_mov_b32_e32 v116, v145
	v_mov_b32_e32 v117, v145
	v_mov_b32_e32 v118, v145
	v_mov_b32_e32 v119, v145
	v_mov_b32_e32 v120, v145
	v_mov_b32_e32 v121, v145
	v_mov_b32_e32 v122, v145
	v_mov_b32_e32 v123, v145
	v_mov_b32_e32 v124, v145
	v_mov_b32_e32 v125, v145
	v_mov_b32_e32 v126, v145
	v_mov_b32_e32 v127, v145
	s_waitcnt lgkmcnt(0)
	s_barrier
	v_readfirstlane_b32 s48, v188
	s_movk_i32 s50, 16
	s_lshr_b32 s52, s2, 3
	s_and_b32 s52, s52, 7
	s_lshl_b32 s52, s52, 9
	s_mov_b32 s53, 0
	v_add_u32_e32 v132, s50, v193
	v_add3_u32 v134, v132, v196, v195
	v_add3_u32 v133, v132, v194, v195
	ds_read_b128 v[164:167], v134 offset:32768
	ds_read_b128 v[172:175], v133
	ds_read_b128 v[168:171], v134 offset:36864
	ds_read_b128 v[176:179], v133 offset:4096
	ds_read_b128 v[180:183], v133 offset:8192
	ds_read_b128 v[212:215], v133 offset:12288
.Lgk1_loop:
	s_and_b32 s33, s43, 0x10000
	s_xor_b32 s49, s33, 0x10000
	s_add_i32 s50, s33, 16
	s_add_u32 s49, s49, s48
	v_add_u32_e32 v132, s50, v197
	v_add3_u32 v134, v132, v196, v195
	v_add3_u32 v133, v132, v194, v195
	ds_read_b128 v[216:219], v134 offset:32768
	ds_read_b128 v[224:227], v133
	ds_read_b128 v[220:223], v134 offset:36864
	ds_read_b128 v[228:231], v133 offset:4096
	ds_read_b128 v[232:235], v133 offset:8192
	ds_read_b128 v[236:239], v133 offset:12288
	v_lshl_add_u64 v[136:137], v[128:129], 0, s[52:53]
	v_lshl_add_u64 v[138:139], v[130:131], 0, s[52:53]
	s_waitcnt lgkmcnt(6)
	v_mfma_f32_32x32x16_bf16 v[112:127], v[164:167], v[172:175], v[112:127]
	s_mov_b32 m0, s49
	v_lshl_add_u64 v[140:141], v[136:137], 0, s[22:23]
	global_load_lds_dwordx4 v[140:141], off
	v_mfma_f32_32x32x16_bf16 v[96:111], v[168:171], v[172:175], v[96:111]
	s_add_u32 m0, s49, 0x8000
	v_lshl_add_u64 v[142:143], v[138:139], 0, s[22:23]
	global_load_lds_dwordx4 v[142:143], off
	v_mfma_f32_32x32x16_bf16 v[80:95], v[164:167], v[176:179], v[80:95]
	s_add_u32 m0, s49, 0x2000
	v_lshl_add_u64 v[140:141], v[136:137], 0, s[24:25]
	global_load_lds_dwordx4 v[140:141], off
	v_mfma_f32_32x32x16_bf16 v[64:79], v[168:171], v[176:179], v[64:79]
	s_add_u32 m0, s49, 0xa000
	v_lshl_add_u64 v[142:143], v[138:139], 0, s[24:25]
	global_load_lds_dwordx4 v[142:143], off
	v_mfma_f32_32x32x16_bf16 v[48:63], v[164:167], v[180:183], v[48:63]
	s_add_u32 m0, s49, 0x4000
	v_lshl_add_u64 v[140:141], v[136:137], 0, s[26:27]
	global_load_lds_dwordx4 v[140:141], off
	v_mfma_f32_32x32x16_bf16 v[32:47], v[168:171], v[180:183], v[32:47]
	s_add_u32 m0, s49, 0xc000
	v_lshl_add_u64 v[142:143], v[138:139], 0, s[26:27]
	global_load_lds_dwordx4 v[142:143], off
	v_mfma_f32_32x32x16_bf16 v[16:31], v[164:167], v[212:215], v[16:31]
	s_add_u32 m0, s49, 0x6000
	v_lshl_add_u64 v[140:141], v[136:137], 0, s[28:29]
	global_load_lds_dwordx4 v[140:141], off
	v_mfma_f32_32x32x16_bf16 v[0:15], v[168:171], v[212:215], v[0:15]
	s_add_u32 m0, s49, 0xe000
	v_lshl_add_u64 v[142:143], v[138:139], 0, s[28:29]
	global_load_lds_dwordx4 v[142:143], off
	v_add_u32_e32 v132, s50, v198
	v_add3_u32 v134, v132, v196, v195
	v_add3_u32 v133, v132, v194, v195
	ds_read_b128 v[164:167], v134 offset:32768
	ds_read_b128 v[172:175], v133
	ds_read_b128 v[168:171], v134 offset:36864
	ds_read_b128 v[176:179], v133 offset:4096
	ds_read_b128 v[180:183], v133 offset:8192
	ds_read_b128 v[212:215], v133 offset:12288
	s_waitcnt lgkmcnt(6)
	v_mfma_f32_32x32x16_bf16 v[112:127], v[216:219], v[224:227], v[112:127]
	v_mfma_f32_32x32x16_bf16 v[96:111], v[220:223], v[224:227], v[96:111]
	v_mfma_f32_32x32x16_bf16 v[80:95], v[216:219], v[228:231], v[80:95]
	v_mfma_f32_32x32x16_bf16 v[64:79], v[220:223], v[228:231], v[64:79]
	v_mfma_f32_32x32x16_bf16 v[48:63], v[216:219], v[232:235], v[48:63]
	v_mfma_f32_32x32x16_bf16 v[32:47], v[220:223], v[232:235], v[32:47]
	v_mfma_f32_32x32x16_bf16 v[16:31], v[216:219], v[236:239], v[16:31]
	v_mfma_f32_32x32x16_bf16 v[0:15], v[220:223], v[236:239], v[0:15]
	v_add_u32_e32 v132, s50, v199
	v_add3_u32 v134, v132, v196, v195
	v_add3_u32 v133, v132, v194, v195
	ds_read_b128 v[216:219], v134 offset:32768
	ds_read_b128 v[224:227], v133
	ds_read_b128 v[220:223], v134 offset:36864
	ds_read_b128 v[228:231], v133 offset:4096
	ds_read_b128 v[232:235], v133 offset:8192
	ds_read_b128 v[236:239], v133 offset:12288
	s_waitcnt lgkmcnt(6)
	v_mfma_f32_32x32x16_bf16 v[112:127], v[164:167], v[172:175], v[112:127]
	v_mfma_f32_32x32x16_bf16 v[96:111], v[168:171], v[172:175], v[96:111]
	v_mfma_f32_32x32x16_bf16 v[80:95], v[164:167], v[176:179], v[80:95]
	v_mfma_f32_32x32x16_bf16 v[64:79], v[168:171], v[176:179], v[64:79]
	v_mfma_f32_32x32x16_bf16 v[48:63], v[164:167], v[180:183], v[48:63]
	v_mfma_f32_32x32x16_bf16 v[32:47], v[168:171], v[180:183], v[32:47]
	v_mfma_f32_32x32x16_bf16 v[16:31], v[164:167], v[212:215], v[16:31]
	v_mfma_f32_32x32x16_bf16 v[0:15], v[168:171], v[212:215], v[0:15]
	s_waitcnt lgkmcnt(0)
	v_mfma_f32_32x32x16_bf16 v[112:127], v[216:219], v[224:227], v[112:127]
	v_mfma_f32_32x32x16_bf16 v[96:111], v[220:223], v[224:227], v[96:111]
	v_mfma_f32_32x32x16_bf16 v[80:95], v[216:219], v[228:231], v[80:95]
	v_mfma_f32_32x32x16_bf16 v[64:79], v[220:223], v[228:231], v[64:79]
	s_add_u32 s4, s4, 0x80
	s_addc_u32 s5, s5, 0
	s_add_i32 s43, s43, 0x10000
	s_add_u32 s52, s52, 0x80
	s_cmp_eq_u32 s52, 0xf80
	s_cselect_b32 s52, 0, s52
	s_xor_b32 s50, s33, 0x10000
	s_add_i32 s50, s50, 16
	s_waitcnt vmcnt(0)
	s_barrier
	v_add_u32_e32 v132, s50, v193
	v_add3_u32 v134, v132, v196, v195
	v_add3_u32 v133, v132, v194, v195
	ds_read_b128 v[164:167], v134 offset:32768
	ds_read_b128 v[172:175], v133
	ds_read_b128 v[168:171], v134 offset:36864
	ds_read_b128 v[176:179], v133 offset:4096
	ds_read_b128 v[180:183], v133 offset:8192
	ds_read_b128 v[212:215], v133 offset:12288
	v_mfma_f32_32x32x16_bf16 v[48:63], v[216:219], v[232:235], v[48:63]
	v_mfma_f32_32x32x16_bf16 v[32:47], v[220:223], v[232:235], v[32:47]
	v_mfma_f32_32x32x16_bf16 v[16:31], v[216:219], v[236:239], v[16:31]
	v_mfma_f32_32x32x16_bf16 v[0:15], v[220:223], v[236:239], v[0:15]
	s_cmpk_lg_i32 s4, 0xf80
	s_cbranch_scc1 .Lgk1_loop
	v_add_u32_e32 v132, s50, v197
	v_add3_u32 v134, v132, v196, v195
	v_add3_u32 v133, v132, v194, v195
	ds_read_b128 v[216:219], v134 offset:32768
	ds_read_b128 v[224:227], v133
	ds_read_b128 v[220:223], v134 offset:36864
	ds_read_b128 v[228:231], v133 offset:4096
	ds_read_b128 v[232:235], v133 offset:8192
	ds_read_b128 v[236:239], v133 offset:12288
	s_waitcnt lgkmcnt(6)
	v_mfma_f32_32x32x16_bf16 v[112:127], v[164:167], v[172:175], v[112:127]
	v_mfma_f32_32x32x16_bf16 v[96:111], v[168:171], v[172:175], v[96:111]
	v_mfma_f32_32x32x16_bf16 v[80:95], v[164:167], v[176:179], v[80:95]
	v_mfma_f32_32x32x16_bf16 v[64:79], v[168:171], v[176:179], v[64:79]
	v_mfma_f32_32x32x16_bf16 v[48:63], v[164:167], v[180:183], v[48:63]
	v_mfma_f32_32x32x16_bf16 v[32:47], v[168:171], v[180:183], v[32:47]
	v_mfma_f32_32x32x16_bf16 v[16:31], v[164:167], v[212:215], v[16:31]
	v_mfma_f32_32x32x16_bf16 v[0:15], v[168:171], v[212:215], v[0:15]
	v_add_u32_e32 v132, s50, v198
	v_add3_u32 v134, v132, v196, v195
	v_add3_u32 v133, v132, v194, v195
	ds_read_b128 v[164:167], v134 offset:32768
	ds_read_b128 v[172:175], v133
	ds_read_b128 v[168:171], v134 offset:36864
	ds_read_b128 v[176:179], v133 offset:4096
	ds_read_b128 v[180:183], v133 offset:8192
	ds_read_b128 v[212:215], v133 offset:12288
	s_waitcnt lgkmcnt(6)
	v_mfma_f32_32x32x16_bf16 v[112:127], v[216:219], v[224:227], v[112:127]
	v_mfma_f32_32x32x16_bf16 v[96:111], v[220:223], v[224:227], v[96:111]
	v_mfma_f32_32x32x16_bf16 v[80:95], v[216:219], v[228:231], v[80:95]
	v_mfma_f32_32x32x16_bf16 v[64:79], v[220:223], v[228:231], v[64:79]
	v_mfma_f32_32x32x16_bf16 v[48:63], v[216:219], v[232:235], v[48:63]
	v_mfma_f32_32x32x16_bf16 v[32:47], v[220:223], v[232:235], v[32:47]
	v_mfma_f32_32x32x16_bf16 v[16:31], v[216:219], v[236:239], v[16:31]
	v_mfma_f32_32x32x16_bf16 v[0:15], v[220:223], v[236:239], v[0:15]
	v_add_u32_e32 v132, s50, v199
	v_add3_u32 v134, v132, v196, v195
	v_add3_u32 v133, v132, v194, v195
	ds_read_b128 v[216:219], v134 offset:32768
	ds_read_b128 v[224:227], v133
	ds_read_b128 v[220:223], v134 offset:36864
	ds_read_b128 v[228:231], v133 offset:4096
	ds_read_b128 v[232:235], v133 offset:8192
	ds_read_b128 v[236:239], v133 offset:12288
	s_waitcnt lgkmcnt(6)
	v_mfma_f32_32x32x16_bf16 v[112:127], v[164:167], v[172:175], v[112:127]
	v_mfma_f32_32x32x16_bf16 v[96:111], v[168:171], v[172:175], v[96:111]
	v_mfma_f32_32x32x16_bf16 v[80:95], v[164:167], v[176:179], v[80:95]
	v_mfma_f32_32x32x16_bf16 v[64:79], v[168:171], v[176:179], v[64:79]
	v_mfma_f32_32x32x16_bf16 v[48:63], v[164:167], v[180:183], v[48:63]
	v_mfma_f32_32x32x16_bf16 v[32:47], v[168:171], v[180:183], v[32:47]
	v_mfma_f32_32x32x16_bf16 v[16:31], v[164:167], v[212:215], v[16:31]
	v_mfma_f32_32x32x16_bf16 v[0:15], v[168:171], v[212:215], v[0:15]
	s_waitcnt vmcnt(0) lgkmcnt(0)
	s_barrier
	v_mfma_f32_32x32x16_bf16 v[112:127], v[216:219], v[224:227], v[112:127]
	v_mfma_f32_32x32x16_bf16 v[96:111], v[220:223], v[224:227], v[96:111]
	v_mfma_f32_32x32x16_bf16 v[80:95], v[216:219], v[228:231], v[80:95]
	v_mfma_f32_32x32x16_bf16 v[64:79], v[220:223], v[228:231], v[64:79]
	v_mfma_f32_32x32x16_bf16 v[48:63], v[216:219], v[232:235], v[48:63]
	v_mfma_f32_32x32x16_bf16 v[32:47], v[220:223], v[232:235], v[32:47]
	v_mfma_f32_32x32x16_bf16 v[16:31], v[216:219], v[236:239], v[16:31]
	v_mfma_f32_32x32x16_bf16 v[0:15], v[220:223], v[236:239], v[0:15]
	s_nop 15

.LBB0_164:
	s_ashr_i32 s33, s30, 2
	s_and_b32 s33, s33, -8
	s_or_b32 s33, s33, s3
	s_ashr_i32 s37, s33, 31
	s_lshr_b32 s37, s37, 29
	s_add_i32 s37, s33, s37
	s_ashr_i32 s39, s37, 3
	s_and_b32 s37, s37, 0x1ffff8
	s_sub_i32 s37, s33, s37
	s_lshl_b32 s38, s30, 8
	s_lshl_b32 s37, s37, 11
	s_and_b32 s38, s38, 0x700
	s_or_b32 s37, s37, s38
	s_lshl_b32 s38, s30, 5
	s_lshl_b32 s40, s39, 10
	s_and_b32 s38, s38, 0x300
	v_add_u32_e32 v0, s37, v149
	s_or_b32 s38, s40, s38
	v_ashrrev_i32_e32 v1, 31, v0
	v_add_u32_e32 v2, s38, v149
	v_lshlrev_b64 v[0:1], 12, v[0:1]
	v_ashrrev_i32_e32 v3, 31, v2
	v_readfirstlane_b32 s41, v150
	v_lshl_add_u64 v[0:1], v[130:131], 0, v[0:1]
	v_lshlrev_b64 v[2:3], 12, v[2:3]
	s_mov_b32 m0, s41
	v_readfirstlane_b32 s41, v128
	v_lshl_add_u64 v[2:3], v[132:133], 0, v[2:3]
	global_load_lds_dwordx4 v[0:1], off
	s_mov_b32 m0, s41
	v_readfirstlane_b32 s41, v160
	global_load_lds_dwordx4 v[2:3], off
	v_lshl_add_u64 v[4:5], v[0:1], 0, s[12:13]
	s_mov_b32 m0, s41
	v_readfirstlane_b32 s41, v161
	global_load_lds_dwordx4 v[4:5], off
	v_lshl_add_u64 v[4:5], v[2:3], 0, s[12:13]
	s_mov_b32 m0, s41
	v_readfirstlane_b32 s41, v162
	global_load_lds_dwordx4 v[4:5], off
	v_lshl_add_u64 v[4:5], v[0:1], 0, s[14:15]
	s_mov_b32 m0, s41
	v_readfirstlane_b32 s41, v163
	global_load_lds_dwordx4 v[4:5], off
	v_lshl_add_u64 v[4:5], v[2:3], 0, s[14:15]
	s_mov_b32 m0, s41
	v_readfirstlane_b32 s41, v164
	global_load_lds_dwordx4 v[4:5], off
	v_lshl_add_u64 v[0:1], v[0:1], 0, s[16:17]
	s_mov_b32 m0, s41
	v_readfirstlane_b32 s41, v165
	global_load_lds_dwordx4 v[0:1], off
	v_lshl_add_u64 v[0:1], v[2:3], 0, s[16:17]
	s_mov_b32 m0, s41
	s_and_b32 s28, s31, 0x700
	global_load_lds_dwordx4 v[0:1], off
	s_lshl_b32 s33, s33, 11
	s_or_b32 s28, s28, s33
	v_add_u32_e32 v0, s28, v149
	s_lshl_b32 s28, s39, 14
	v_subrev_u32_e32 v0, s28, v0
	s_and_b32 s29, s35, 0x300
	v_ashrrev_i32_e32 v1, 31, v0
	v_lshlrev_b64 v[0:1], 12, v[0:1]
	s_or_b32 s28, s29, s40
	v_lshl_add_u64 v[138:139], v[134:135], 0, v[0:1]
	v_add_u32_e32 v0, s28, v149
	v_ashrrev_i32_e32 v1, 31, v0
	v_lshlrev_b64 v[0:1], 12, v[0:1]
	v_lshl_add_u64 v[140:141], v[136:137], 0, v[0:1]
	s_mov_b32 s39, 0
	s_mov_b64 s[28:29], 0
	v_mov_b32_e32 v0, 0
	v_mov_b32_e32 v1, v129
	v_mov_b32_e32 v2, v129
	v_mov_b32_e32 v3, v129
	v_mov_b32_e32 v4, v129
	v_mov_b32_e32 v5, v129
	v_mov_b32_e32 v6, v129
	v_mov_b32_e32 v7, v129
	v_mov_b32_e32 v8, v129
	v_mov_b32_e32 v9, v129
	v_mov_b32_e32 v10, v129
	v_mov_b32_e32 v11, v129
	v_mov_b32_e32 v12, v129
	v_mov_b32_e32 v13, v129
	v_mov_b32_e32 v14, v129
	v_mov_b32_e32 v15, v129
	v_mov_b32_e32 v16, 0
	v_mov_b32_e32 v17, v129
	v_mov_b32_e32 v18, v129
	v_mov_b32_e32 v19, v129
	v_mov_b32_e32 v20, v129
	v_mov_b32_e32 v21, v129
	v_mov_b32_e32 v22, v129
	v_mov_b32_e32 v23, v129
	v_mov_b32_e32 v24, v129
	v_mov_b32_e32 v25, v129
	v_mov_b32_e32 v26, v129
	v_mov_b32_e32 v27, v129
	v_mov_b32_e32 v28, v129
	v_mov_b32_e32 v29, v129
	v_mov_b32_e32 v30, v129
	v_mov_b32_e32 v31, v129
	v_mov_b32_e32 v32, 0
	v_mov_b32_e32 v33, v129
	v_mov_b32_e32 v34, v129
	v_mov_b32_e32 v35, v129
	v_mov_b32_e32 v36, v129
	v_mov_b32_e32 v37, v129
	v_mov_b32_e32 v38, v129
	v_mov_b32_e32 v39, v129
	v_mov_b32_e32 v40, v129
	v_mov_b32_e32 v41, v129
	v_mov_b32_e32 v42, v129
	v_mov_b32_e32 v43, v129
	v_mov_b32_e32 v44, v129
	v_mov_b32_e32 v45, v129
	v_mov_b32_e32 v46, v129
	v_mov_b32_e32 v47, v129
	v_mov_b32_e32 v48, 0
	v_mov_b32_e32 v49, v129
	v_mov_b32_e32 v50, v129
	v_mov_b32_e32 v51, v129
	v_mov_b32_e32 v52, v129
	v_mov_b32_e32 v53, v129
	v_mov_b32_e32 v54, v129
	v_mov_b32_e32 v55, v129
	v_mov_b32_e32 v56, v129
	v_mov_b32_e32 v57, v129
	v_mov_b32_e32 v58, v129
	v_mov_b32_e32 v59, v129
	v_mov_b32_e32 v60, v129
	v_mov_b32_e32 v61, v129
	v_mov_b32_e32 v62, v129
	v_mov_b32_e32 v63, v129
	v_mov_b32_e32 v64, 0
	v_mov_b32_e32 v65, v129
	v_mov_b32_e32 v66, v129
	v_mov_b32_e32 v67, v129
	v_mov_b32_e32 v68, v129
	v_mov_b32_e32 v69, v129
	v_mov_b32_e32 v70, v129
	v_mov_b32_e32 v71, v129
	v_mov_b32_e32 v72, v129
	v_mov_b32_e32 v73, v129
	v_mov_b32_e32 v74, v129
	v_mov_b32_e32 v75, v129
	v_mov_b32_e32 v76, v129
	v_mov_b32_e32 v77, v129
	v_mov_b32_e32 v78, v129
	v_mov_b32_e32 v79, v129
	v_mov_b32_e32 v80, 0
	v_mov_b32_e32 v81, v129
	v_mov_b32_e32 v82, v129
	v_mov_b32_e32 v83, v129
	v_mov_b32_e32 v84, v129
	v_mov_b32_e32 v85, v129
	v_mov_b32_e32 v86, v129
	v_mov_b32_e32 v87, v129
	v_mov_b32_e32 v88, v129
	v_mov_b32_e32 v89, v129
	v_mov_b32_e32 v90, v129
	v_mov_b32_e32 v91, v129
	v_mov_b32_e32 v92, v129
	v_mov_b32_e32 v93, v129
	v_mov_b32_e32 v94, v129
	v_mov_b32_e32 v95, v129
	v_mov_b32_e32 v96, 0
	v_mov_b32_e32 v97, v129
	v_mov_b32_e32 v98, v129
	v_mov_b32_e32 v99, v129
	v_mov_b32_e32 v100, v129
	v_mov_b32_e32 v101, v129
	v_mov_b32_e32 v102, v129
	v_mov_b32_e32 v103, v129
	v_mov_b32_e32 v104, v129
	v_mov_b32_e32 v105, v129
	v_mov_b32_e32 v106, v129
	v_mov_b32_e32 v107, v129
	v_mov_b32_e32 v108, v129
	v_mov_b32_e32 v109, v129
	v_mov_b32_e32 v110, v129
	v_mov_b32_e32 v111, v129
	v_mov_b32_e32 v112, 0
	v_mov_b32_e32 v113, v129
	v_mov_b32_e32 v114, v129
	v_mov_b32_e32 v115, v129
	v_mov_b32_e32 v116, v129
	v_mov_b32_e32 v117, v129
	v_mov_b32_e32 v118, v129
	v_mov_b32_e32 v119, v129
	v_mov_b32_e32 v120, v129
	v_mov_b32_e32 v121, v129
	v_mov_b32_e32 v122, v129
	v_mov_b32_e32 v123, v129
	v_mov_b32_e32 v124, v129
	v_mov_b32_e32 v125, v129
	v_mov_b32_e32 v126, v129
	v_mov_b32_e32 v127, v129
	s_waitcnt vmcnt(0) lgkmcnt(0)
	s_barrier
	v_readfirstlane_b32 s48, v150
	s_movk_i32 s50, 16
	s_lshr_b32 s52, s2, 3
	s_and_b32 s52, s52, 7
	s_lshl_b32 s52, s52, 9
	s_mov_b32 s53, 0
	v_add_u32_e32 v142, s50, v153
	v_add3_u32 v144, v142, v156, v155
	v_add3_u32 v143, v142, v154, v155
	ds_read_b128 v[188:191], v144 offset:32768
	ds_read_b128 v[196:199], v143
	ds_read_b128 v[192:195], v144 offset:36864
	ds_read_b128 v[200:203], v143 offset:4096
	ds_read_b128 v[204:207], v143 offset:8192
	ds_read_b128 v[208:211], v143 offset:12288
.Lgk2_loop:
	s_and_b32 s33, s39, 0x10000
	s_xor_b32 s49, s33, 0x10000
	s_add_i32 s50, s33, 16
	s_add_u32 s49, s49, s48
	v_add_u32_e32 v142, s50, v157
	v_add3_u32 v144, v142, v156, v155
	v_add3_u32 v143, v142, v154, v155
	ds_read_b128 v[212:215], v144 offset:32768
	ds_read_b128 v[220:223], v143
	ds_read_b128 v[216:219], v144 offset:36864
	ds_read_b128 v[224:227], v143 offset:4096
	ds_read_b128 v[228:231], v143 offset:8192
	ds_read_b128 v[232:235], v143 offset:12288
	v_lshl_add_u64 v[166:167], v[138:139], 0, s[52:53]
	v_lshl_add_u64 v[168:169], v[140:141], 0, s[52:53]
	s_waitcnt lgkmcnt(6)
	v_mfma_f32_32x32x16_bf16 v[112:127], v[188:191], v[196:199], v[112:127]
	s_mov_b32 m0, s49
	v_lshl_add_u64 v[170:171], v[166:167], 0, s[18:19]
	global_load_lds_dwordx4 v[170:171], off
	v_mfma_f32_32x32x16_bf16 v[96:111], v[192:195], v[196:199], v[96:111]
	s_add_u32 m0, s49, 0x8000
	v_lshl_add_u64 v[172:173], v[168:169], 0, s[18:19]
	global_load_lds_dwordx4 v[172:173], off
	v_mfma_f32_32x32x16_bf16 v[80:95], v[188:191], v[200:203], v[80:95]
	s_add_u32 m0, s49, 0x2000
	v_lshl_add_u64 v[170:171], v[166:167], 0, s[20:21]
	global_load_lds_dwordx4 v[170:171], off
	v_mfma_f32_32x32x16_bf16 v[64:79], v[192:195], v[200:203], v[64:79]
	s_add_u32 m0, s49, 0xa000
	v_lshl_add_u64 v[172:173], v[168:169], 0, s[20:21]
	global_load_lds_dwordx4 v[172:173], off
	v_mfma_f32_32x32x16_bf16 v[48:63], v[188:191], v[204:207], v[48:63]
	s_add_u32 m0, s49, 0x4000
	v_lshl_add_u64 v[170:171], v[166:167], 0, s[22:23]
	global_load_lds_dwordx4 v[170:171], off
	v_mfma_f32_32x32x16_bf16 v[32:47], v[192:195], v[204:207], v[32:47]
	s_add_u32 m0, s49, 0xc000
	v_lshl_add_u64 v[172:173], v[168:169], 0, s[22:23]
	global_load_lds_dwordx4 v[172:173], off
	v_mfma_f32_32x32x16_bf16 v[16:31], v[188:191], v[208:211], v[16:31]
	s_add_u32 m0, s49, 0x6000
	v_lshl_add_u64 v[170:171], v[166:167], 0, s[24:25]
	global_load_lds_dwordx4 v[170:171], off
	v_mfma_f32_32x32x16_bf16 v[0:15], v[192:195], v[208:211], v[0:15]
	s_add_u32 m0, s49, 0xe000
	v_lshl_add_u64 v[172:173], v[168:169], 0, s[24:25]
	global_load_lds_dwordx4 v[172:173], off
	v_add_u32_e32 v142, s50, v158
	v_add3_u32 v144, v142, v156, v155
	v_add3_u32 v143, v142, v154, v155
	ds_read_b128 v[188:191], v144 offset:32768
	ds_read_b128 v[196:199], v143
	ds_read_b128 v[192:195], v144 offset:36864
	ds_read_b128 v[200:203], v143 offset:4096
	ds_read_b128 v[204:207], v143 offset:8192
	ds_read_b128 v[208:211], v143 offset:12288
	s_waitcnt lgkmcnt(6)
	v_mfma_f32_32x32x16_bf16 v[112:127], v[212:215], v[220:223], v[112:127]
	v_mfma_f32_32x32x16_bf16 v[96:111], v[216:219], v[220:223], v[96:111]
	v_mfma_f32_32x32x16_bf16 v[80:95], v[212:215], v[224:227], v[80:95]
	v_mfma_f32_32x32x16_bf16 v[64:79], v[216:219], v[224:227], v[64:79]
	v_mfma_f32_32x32x16_bf16 v[48:63], v[212:215], v[228:231], v[48:63]
	v_mfma_f32_32x32x16_bf16 v[32:47], v[216:219], v[228:231], v[32:47]
	v_mfma_f32_32x32x16_bf16 v[16:31], v[212:215], v[232:235], v[16:31]
	v_mfma_f32_32x32x16_bf16 v[0:15], v[216:219], v[232:235], v[0:15]
	v_add_u32_e32 v142, s50, v159
	v_add3_u32 v144, v142, v156, v155
	v_add3_u32 v143, v142, v154, v155
	ds_read_b128 v[212:215], v144 offset:32768
	ds_read_b128 v[220:223], v143
	ds_read_b128 v[216:219], v144 offset:36864
	ds_read_b128 v[224:227], v143 offset:4096
	ds_read_b128 v[228:231], v143 offset:8192
	ds_read_b128 v[232:235], v143 offset:12288
	s_waitcnt lgkmcnt(6)
	v_mfma_f32_32x32x16_bf16 v[112:127], v[188:191], v[196:199], v[112:127]
	v_mfma_f32_32x32x16_bf16 v[96:111], v[192:195], v[196:199], v[96:111]
	v_mfma_f32_32x32x16_bf16 v[80:95], v[188:191], v[200:203], v[80:95]
	v_mfma_f32_32x32x16_bf16 v[64:79], v[192:195], v[200:203], v[64:79]
	v_mfma_f32_32x32x16_bf16 v[48:63], v[188:191], v[204:207], v[48:63]
	v_mfma_f32_32x32x16_bf16 v[32:47], v[192:195], v[204:207], v[32:47]
	v_mfma_f32_32x32x16_bf16 v[16:31], v[188:191], v[208:211], v[16:31]
	v_mfma_f32_32x32x16_bf16 v[0:15], v[192:195], v[208:211], v[0:15]
	s_waitcnt lgkmcnt(0)
	v_mfma_f32_32x32x16_bf16 v[112:127], v[212:215], v[220:223], v[112:127]
	v_mfma_f32_32x32x16_bf16 v[96:111], v[216:219], v[220:223], v[96:111]
	v_mfma_f32_32x32x16_bf16 v[80:95], v[212:215], v[224:227], v[80:95]
	v_mfma_f32_32x32x16_bf16 v[64:79], v[216:219], v[224:227], v[64:79]
	s_add_u32 s28, s28, 0x80
	s_addc_u32 s29, s29, 0
	s_add_i32 s39, s39, 0x10000
	s_add_u32 s52, s52, 0x80
	s_cmp_eq_u32 s52, 0xf80
	s_cselect_b32 s52, 0, s52
	s_xor_b32 s50, s33, 0x10000
	s_add_i32 s50, s50, 16
	s_waitcnt vmcnt(0)
	s_barrier
	v_add_u32_e32 v142, s50, v153
	v_add3_u32 v144, v142, v156, v155
	v_add3_u32 v143, v142, v154, v155
	ds_read_b128 v[188:191], v144 offset:32768
	ds_read_b128 v[196:199], v143
	ds_read_b128 v[192:195], v144 offset:36864
	ds_read_b128 v[200:203], v143 offset:4096
	ds_read_b128 v[204:207], v143 offset:8192
	ds_read_b128 v[208:211], v143 offset:12288
	v_mfma_f32_32x32x16_bf16 v[48:63], v[212:215], v[228:231], v[48:63]
	v_mfma_f32_32x32x16_bf16 v[32:47], v[216:219], v[228:231], v[32:47]
	v_mfma_f32_32x32x16_bf16 v[16:31], v[212:215], v[232:235], v[16:31]
	v_mfma_f32_32x32x16_bf16 v[0:15], v[216:219], v[232:235], v[0:15]
	s_cmpk_lg_i32 s28, 0xf80
	s_cbranch_scc1 .Lgk2_loop
	v_add_u32_e32 v142, s50, v157
	v_add3_u32 v144, v142, v156, v155
	v_add3_u32 v143, v142, v154, v155
	ds_read_b128 v[212:215], v144 offset:32768
	ds_read_b128 v[220:223], v143
	ds_read_b128 v[216:219], v144 offset:36864
	ds_read_b128 v[224:227], v143 offset:4096
	ds_read_b128 v[228:231], v143 offset:8192
	ds_read_b128 v[232:235], v143 offset:12288
	s_waitcnt lgkmcnt(6)
	v_mfma_f32_32x32x16_bf16 v[112:127], v[188:191], v[196:199], v[112:127]
	v_mfma_f32_32x32x16_bf16 v[96:111], v[192:195], v[196:199], v[96:111]
	v_mfma_f32_32x32x16_bf16 v[80:95], v[188:191], v[200:203], v[80:95]
	v_mfma_f32_32x32x16_bf16 v[64:79], v[192:195], v[200:203], v[64:79]
	v_mfma_f32_32x32x16_bf16 v[48:63], v[188:191], v[204:207], v[48:63]
	v_mfma_f32_32x32x16_bf16 v[32:47], v[192:195], v[204:207], v[32:47]
	v_mfma_f32_32x32x16_bf16 v[16:31], v[188:191], v[208:211], v[16:31]
	v_mfma_f32_32x32x16_bf16 v[0:15], v[192:195], v[208:211], v[0:15]
	v_add_u32_e32 v142, s50, v158
	v_add3_u32 v144, v142, v156, v155
	v_add3_u32 v143, v142, v154, v155
	ds_read_b128 v[188:191], v144 offset:32768
	ds_read_b128 v[196:199], v143
	ds_read_b128 v[192:195], v144 offset:36864
	ds_read_b128 v[200:203], v143 offset:4096
	ds_read_b128 v[204:207], v143 offset:8192
	ds_read_b128 v[208:211], v143 offset:12288
	s_waitcnt lgkmcnt(6)
	v_mfma_f32_32x32x16_bf16 v[112:127], v[212:215], v[220:223], v[112:127]
	v_mfma_f32_32x32x16_bf16 v[96:111], v[216:219], v[220:223], v[96:111]
	v_mfma_f32_32x32x16_bf16 v[80:95], v[212:215], v[224:227], v[80:95]
	v_mfma_f32_32x32x16_bf16 v[64:79], v[216:219], v[224:227], v[64:79]
	v_mfma_f32_32x32x16_bf16 v[48:63], v[212:215], v[228:231], v[48:63]
	v_mfma_f32_32x32x16_bf16 v[32:47], v[216:219], v[228:231], v[32:47]
	v_mfma_f32_32x32x16_bf16 v[16:31], v[212:215], v[232:235], v[16:31]
	v_mfma_f32_32x32x16_bf16 v[0:15], v[216:219], v[232:235], v[0:15]
	v_add_u32_e32 v142, s50, v159
	v_add3_u32 v144, v142, v156, v155
	v_add3_u32 v143, v142, v154, v155
	ds_read_b128 v[212:215], v144 offset:32768
	ds_read_b128 v[220:223], v143
	ds_read_b128 v[216:219], v144 offset:36864
	ds_read_b128 v[224:227], v143 offset:4096
	ds_read_b128 v[228:231], v143 offset:8192
	ds_read_b128 v[232:235], v143 offset:12288
	s_waitcnt lgkmcnt(6)
	v_mfma_f32_32x32x16_bf16 v[112:127], v[188:191], v[196:199], v[112:127]
	v_mfma_f32_32x32x16_bf16 v[96:111], v[192:195], v[196:199], v[96:111]
	v_mfma_f32_32x32x16_bf16 v[80:95], v[188:191], v[200:203], v[80:95]
	v_mfma_f32_32x32x16_bf16 v[64:79], v[192:195], v[200:203], v[64:79]
	v_mfma_f32_32x32x16_bf16 v[48:63], v[188:191], v[204:207], v[48:63]
	v_mfma_f32_32x32x16_bf16 v[32:47], v[192:195], v[204:207], v[32:47]
	v_mfma_f32_32x32x16_bf16 v[16:31], v[188:191], v[208:211], v[16:31]
	v_mfma_f32_32x32x16_bf16 v[0:15], v[192:195], v[208:211], v[0:15]
	s_waitcnt vmcnt(0) lgkmcnt(0)
	s_barrier
	v_mfma_f32_32x32x16_bf16 v[112:127], v[212:215], v[220:223], v[112:127]
	v_mfma_f32_32x32x16_bf16 v[96:111], v[216:219], v[220:223], v[96:111]
	v_mfma_f32_32x32x16_bf16 v[80:95], v[212:215], v[224:227], v[80:95]
	v_mfma_f32_32x32x16_bf16 v[64:79], v[216:219], v[224:227], v[64:79]
	v_mfma_f32_32x32x16_bf16 v[48:63], v[212:215], v[228:231], v[48:63]
	v_mfma_f32_32x32x16_bf16 v[32:47], v[216:219], v[228:231], v[32:47]
	v_mfma_f32_32x32x16_bf16 v[16:31], v[212:215], v[232:235], v[16:31]
	v_mfma_f32_32x32x16_bf16 v[0:15], v[216:219], v[232:235], v[0:15]
	s_nop 15
	s_branch .LBB0_163

.LBB0_198:
	s_ashr_i32 s27, s30, 2
	s_and_b32 s27, s27, -8
	s_or_b32 s33, s27, s3
	s_ashr_i32 s27, s33, 31
	s_lshr_b32 s27, s27, 29
	s_add_i32 s27, s33, s27
	s_ashr_i32 s46, s27, 3
	s_bfe_u32 s26, s30, 0x20003
	s_and_b32 s27, s27, 0x1ffff8
	s_lshl_b32 s47, s46, 2
	s_lshl_b32 s29, s26, 8
	s_sub_i32 s27, s33, s27
	s_or_b32 s26, s47, s26
	s_lshl_b32 s47, s30, 8
	s_lshl_b32 s27, s27, 11
	s_and_b32 s47, s47, 0x700
	s_or_b32 s27, s27, s47
	v_add_u32_e32 v0, s27, v142
	v_ashrrev_i32_e32 v1, 31, v0
	v_lshl_add_u32 v2, s26, 8, v142
	v_lshlrev_b64 v[0:1], 12, v[0:1]
	v_ashrrev_i32_e32 v3, 31, v2
	v_readfirstlane_b32 s47, v143
	v_add_u32_e32 v4, 0x8000, v143
	v_lshl_add_u64 v[0:1], v[130:131], 0, v[0:1]
	v_lshlrev_b64 v[2:3], 12, v[2:3]
	s_mov_b32 m0, s47
	v_readfirstlane_b32 s47, v4
	v_add_u32_e32 v6, 0x2000, v143
	v_lshl_add_u64 v[2:3], v[132:133], 0, v[2:3]
	global_load_lds_dwordx4 v[0:1], off
	s_mov_b32 m0, s47
	v_readfirstlane_b32 s47, v6
	v_add_u32_e32 v6, 0xa000, v143
	global_load_lds_dwordx4 v[2:3], off
	v_lshl_add_u64 v[4:5], v[0:1], 0, s[12:13]
	s_mov_b32 m0, s47
	v_readfirstlane_b32 s47, v6
	v_add_u32_e32 v6, 0x4000, v143
	global_load_lds_dwordx4 v[4:5], off
	v_lshl_add_u64 v[4:5], v[2:3], 0, s[12:13]
	s_mov_b32 m0, s47
	v_readfirstlane_b32 s47, v6
	v_add_u32_e32 v6, 0xc000, v143
	global_load_lds_dwordx4 v[4:5], off
	v_lshl_add_u64 v[4:5], v[0:1], 0, s[14:15]
	s_mov_b32 m0, s47
	v_readfirstlane_b32 s47, v6
	global_load_lds_dwordx4 v[4:5], off
	v_lshl_add_u64 v[4:5], v[2:3], 0, s[14:15]
	s_mov_b32 m0, s47
	v_lshl_add_u64 v[0:1], v[0:1], 0, s[16:17]
	global_load_lds_dwordx4 v[4:5], off
	v_add_u32_e32 v4, 0x6000, v143
	s_and_b32 s28, s34, 0x700
	v_readfirstlane_b32 s47, v4
	s_mov_b32 m0, s47
	s_lshl_b32 s33, s33, 11
	global_load_lds_dwordx4 v[0:1], off
	v_lshl_add_u64 v[0:1], v[2:3], 0, s[16:17]
	v_add_u32_e32 v2, 0xe000, v143
	s_or_b32 s28, s28, s33
	v_readfirstlane_b32 s47, v2
	s_mov_b32 m0, s47
	v_mov_b32_e32 v2, v129
	global_load_lds_dwordx4 v[0:1], off
	v_add_u32_e32 v0, s28, v142
	s_lshl_b32 s28, s46, 14
	v_subrev_u32_e32 v0, s28, v0
	v_ashrrev_i32_e32 v1, 31, v0
	s_lshl_b32 s28, s46, 10
	v_lshlrev_b64 v[0:1], 12, v[0:1]
	s_or_b32 s28, s29, s28
	v_lshl_add_u64 v[138:139], v[134:135], 0, v[0:1]
	v_add_u32_e32 v0, s28, v142
	v_ashrrev_i32_e32 v1, 31, v0
	v_lshlrev_b64 v[0:1], 12, v[0:1]
	v_lshl_add_u64 v[140:141], v[136:137], 0, v[0:1]
	s_mov_b64 s[28:29], 0
	s_mov_b32 s46, 0
	v_mov_b32_e32 v0, 0
	v_mov_b32_e32 v1, v129
	v_mov_b32_e32 v3, v129
	v_mov_b32_e32 v4, v129
	v_mov_b32_e32 v5, v129
	v_mov_b32_e32 v6, v129
	v_mov_b32_e32 v7, v129
	v_mov_b32_e32 v8, v129
	v_mov_b32_e32 v9, v129
	v_mov_b32_e32 v10, v129
	v_mov_b32_e32 v11, v129
	v_mov_b32_e32 v12, v129
	v_mov_b32_e32 v13, v129
	v_mov_b32_e32 v14, v129
	v_mov_b32_e32 v15, v129
	v_mov_b32_e32 v16, 0
	v_mov_b32_e32 v17, v129
	v_mov_b32_e32 v18, v129
	v_mov_b32_e32 v19, v129
	v_mov_b32_e32 v20, v129
	v_mov_b32_e32 v21, v129
	v_mov_b32_e32 v22, v129
	v_mov_b32_e32 v23, v129
	v_mov_b32_e32 v24, v129
	v_mov_b32_e32 v25, v129
	v_mov_b32_e32 v26, v129
	v_mov_b32_e32 v27, v129
	v_mov_b32_e32 v28, v129
	v_mov_b32_e32 v29, v129
	v_mov_b32_e32 v30, v129
	v_mov_b32_e32 v31, v129
	v_mov_b32_e32 v32, 0
	v_mov_b32_e32 v33, v129
	v_mov_b32_e32 v34, v129
	v_mov_b32_e32 v35, v129
	v_mov_b32_e32 v36, v129
	v_mov_b32_e32 v37, v129
	v_mov_b32_e32 v38, v129
	v_mov_b32_e32 v39, v129
	v_mov_b32_e32 v40, v129
	v_mov_b32_e32 v41, v129
	v_mov_b32_e32 v42, v129
	v_mov_b32_e32 v43, v129
	v_mov_b32_e32 v44, v129
	v_mov_b32_e32 v45, v129
	v_mov_b32_e32 v46, v129
	v_mov_b32_e32 v47, v129
	v_mov_b32_e32 v48, 0
	v_mov_b32_e32 v49, v129
	v_mov_b32_e32 v50, v129
	v_mov_b32_e32 v51, v129
	v_mov_b32_e32 v52, v129
	v_mov_b32_e32 v53, v129
	v_mov_b32_e32 v54, v129
	v_mov_b32_e32 v55, v129
	v_mov_b32_e32 v56, v129
	v_mov_b32_e32 v57, v129
	v_mov_b32_e32 v58, v129
	v_mov_b32_e32 v59, v129
	v_mov_b32_e32 v60, v129
	v_mov_b32_e32 v61, v129
	v_mov_b32_e32 v62, v129
	v_mov_b32_e32 v63, v129
	v_mov_b32_e32 v64, 0
	v_mov_b32_e32 v65, v129
	v_mov_b32_e32 v66, v129
	v_mov_b32_e32 v67, v129
	v_mov_b32_e32 v68, v129
	v_mov_b32_e32 v69, v129
	v_mov_b32_e32 v70, v129
	v_mov_b32_e32 v71, v129
	v_mov_b32_e32 v72, v129
	v_mov_b32_e32 v73, v129
	v_mov_b32_e32 v74, v129
	v_mov_b32_e32 v75, v129
	v_mov_b32_e32 v76, v129
	v_mov_b32_e32 v77, v129
	v_mov_b32_e32 v78, v129
	v_mov_b32_e32 v79, v129
	v_mov_b32_e32 v80, 0
	v_mov_b32_e32 v81, v129
	v_mov_b32_e32 v82, v129
	v_mov_b32_e32 v83, v129
	v_mov_b32_e32 v84, v129
	v_mov_b32_e32 v85, v129
	v_mov_b32_e32 v86, v129
	v_mov_b32_e32 v87, v129
	v_mov_b32_e32 v88, v129
	v_mov_b32_e32 v89, v129
	v_mov_b32_e32 v90, v129
	v_mov_b32_e32 v91, v129
	v_mov_b32_e32 v92, v129
	v_mov_b32_e32 v93, v129
	v_mov_b32_e32 v94, v129
	v_mov_b32_e32 v95, v129
	v_mov_b32_e32 v96, 0
	v_mov_b32_e32 v97, v129
	v_mov_b32_e32 v98, v129
	v_mov_b32_e32 v99, v129
	v_mov_b32_e32 v100, v129
	v_mov_b32_e32 v101, v129
	v_mov_b32_e32 v102, v129
	v_mov_b32_e32 v103, v129
	v_mov_b32_e32 v104, v129
	v_mov_b32_e32 v105, v129
	v_mov_b32_e32 v106, v129
	v_mov_b32_e32 v107, v129
	v_mov_b32_e32 v108, v129
	v_mov_b32_e32 v109, v129
	v_mov_b32_e32 v110, v129
	v_mov_b32_e32 v111, v129
	v_mov_b32_e32 v112, 0
	v_mov_b32_e32 v113, v129
	v_mov_b32_e32 v114, v129
	v_mov_b32_e32 v115, v129
	v_mov_b32_e32 v116, v129
	v_mov_b32_e32 v117, v129
	v_mov_b32_e32 v118, v129
	v_mov_b32_e32 v119, v129
	v_mov_b32_e32 v120, v129
	v_mov_b32_e32 v121, v129
	v_mov_b32_e32 v122, v129
	v_mov_b32_e32 v123, v129
	v_mov_b32_e32 v124, v129
	v_mov_b32_e32 v125, v129
	v_mov_b32_e32 v126, v129
	v_mov_b32_e32 v127, v129
	s_waitcnt vmcnt(0) lgkmcnt(0)
	s_barrier
	v_readfirstlane_b32 s48, v143
	s_movk_i32 s50, 16
	s_lshr_b32 s52, s2, 3
	s_and_b32 s52, s52, 7
	s_lshl_b32 s52, s52, 9
	s_mov_b32 s53, 0
	v_add_u32_e32 v240, s50, v147
	v_add_u32_e32 v243, v240, v150
	v_add3_u32 v241, v240, v148, v149
	ds_read_b128 v[192:195], v243 offset:32768
	ds_read_b128 v[200:203], v241
	ds_read_b128 v[196:199], v243 offset:36864
	ds_read_b128 v[204:207], v241 offset:4096
	ds_read_b128 v[208:211], v241 offset:8192
	ds_read_b128 v[212:215], v241 offset:12288
.Lgk3_loop:
	s_and_b32 s33, s46, 0x10000
	s_xor_b32 s49, s33, 0x10000
	s_add_i32 s50, s33, 16
	s_add_u32 s49, s49, s48
	v_add_u32_e32 v240, s50, v151
	v_add_u32_e32 v243, v240, v150
	v_add3_u32 v241, v240, v148, v149
	ds_read_b128 v[216:219], v243 offset:32768
	ds_read_b128 v[224:227], v241
	ds_read_b128 v[220:223], v243 offset:36864
	ds_read_b128 v[228:231], v241 offset:4096
	ds_read_b128 v[232:235], v241 offset:8192
	ds_read_b128 v[236:239], v241 offset:12288
	v_lshl_add_u64 v[244:245], v[138:139], 0, s[52:53]
	v_lshl_add_u64 v[246:247], v[140:141], 0, s[52:53]
	s_waitcnt lgkmcnt(6)
	v_mfma_f32_32x32x16_bf16 v[112:127], v[192:195], v[200:203], v[112:127]
	s_mov_b32 m0, s49
	v_lshl_add_u64 v[248:249], v[244:245], 0, s[18:19]
	global_load_lds_dwordx4 v[248:249], off
	v_mfma_f32_32x32x16_bf16 v[96:111], v[196:199], v[200:203], v[96:111]
	s_add_u32 m0, s49, 0x8000
	v_lshl_add_u64 v[250:251], v[246:247], 0, s[18:19]
	global_load_lds_dwordx4 v[250:251], off
	v_mfma_f32_32x32x16_bf16 v[80:95], v[192:195], v[204:207], v[80:95]
	s_add_u32 m0, s49, 0x2000
	v_lshl_add_u64 v[248:249], v[244:245], 0, s[20:21]
	global_load_lds_dwordx4 v[248:249], off
	v_mfma_f32_32x32x16_bf16 v[64:79], v[196:199], v[204:207], v[64:79]
	s_add_u32 m0, s49, 0xa000
	v_lshl_add_u64 v[250:251], v[246:247], 0, s[20:21]
	global_load_lds_dwordx4 v[250:251], off
	v_mfma_f32_32x32x16_bf16 v[48:63], v[192:195], v[208:211], v[48:63]
	s_add_u32 m0, s49, 0x4000
	v_lshl_add_u64 v[248:249], v[244:245], 0, s[22:23]
	global_load_lds_dwordx4 v[248:249], off
	v_mfma_f32_32x32x16_bf16 v[32:47], v[196:199], v[208:211], v[32:47]
	s_add_u32 m0, s49, 0xc000
	v_lshl_add_u64 v[250:251], v[246:247], 0, s[22:23]
	global_load_lds_dwordx4 v[250:251], off
	v_mfma_f32_32x32x16_bf16 v[16:31], v[192:195], v[212:215], v[16:31]
	s_add_u32 m0, s49, 0x6000
	v_lshl_add_u64 v[248:249], v[244:245], 0, s[24:25]
	global_load_lds_dwordx4 v[248:249], off
	v_mfma_f32_32x32x16_bf16 v[0:15], v[196:199], v[212:215], v[0:15]
	s_add_u32 m0, s49, 0xe000
	v_lshl_add_u64 v[250:251], v[246:247], 0, s[24:25]
	global_load_lds_dwordx4 v[250:251], off
	v_add_u32_e32 v240, s50, v152
	v_add_u32_e32 v243, v240, v150
	v_add3_u32 v241, v240, v148, v149
	ds_read_b128 v[192:195], v243 offset:32768
	ds_read_b128 v[200:203], v241
	ds_read_b128 v[196:199], v243 offset:36864
	ds_read_b128 v[204:207], v241 offset:4096
	ds_read_b128 v[208:211], v241 offset:8192
	ds_read_b128 v[212:215], v241 offset:12288
	s_waitcnt lgkmcnt(6)
	v_mfma_f32_32x32x16_bf16 v[112:127], v[216:219], v[224:227], v[112:127]
	v_mfma_f32_32x32x16_bf16 v[96:111], v[220:223], v[224:227], v[96:111]
	v_mfma_f32_32x32x16_bf16 v[80:95], v[216:219], v[228:231], v[80:95]
	v_mfma_f32_32x32x16_bf16 v[64:79], v[220:223], v[228:231], v[64:79]
	v_mfma_f32_32x32x16_bf16 v[48:63], v[216:219], v[232:235], v[48:63]
	v_mfma_f32_32x32x16_bf16 v[32:47], v[220:223], v[232:235], v[32:47]
	v_mfma_f32_32x32x16_bf16 v[16:31], v[216:219], v[236:239], v[16:31]
	v_mfma_f32_32x32x16_bf16 v[0:15], v[220:223], v[236:239], v[0:15]
	v_add_u32_e32 v240, s50, v153
	v_add_u32_e32 v243, v240, v150
	v_add3_u32 v241, v240, v148, v149
	ds_read_b128 v[216:219], v243 offset:32768
	ds_read_b128 v[224:227], v241
	ds_read_b128 v[220:223], v243 offset:36864
	ds_read_b128 v[228:231], v241 offset:4096
	ds_read_b128 v[232:235], v241 offset:8192
	ds_read_b128 v[236:239], v241 offset:12288
	s_waitcnt lgkmcnt(6)
	v_mfma_f32_32x32x16_bf16 v[112:127], v[192:195], v[200:203], v[112:127]
	v_mfma_f32_32x32x16_bf16 v[96:111], v[196:199], v[200:203], v[96:111]
	v_mfma_f32_32x32x16_bf16 v[80:95], v[192:195], v[204:207], v[80:95]
	v_mfma_f32_32x32x16_bf16 v[64:79], v[196:199], v[204:207], v[64:79]
	v_mfma_f32_32x32x16_bf16 v[48:63], v[192:195], v[208:211], v[48:63]
	v_mfma_f32_32x32x16_bf16 v[32:47], v[196:199], v[208:211], v[32:47]
	v_mfma_f32_32x32x16_bf16 v[16:31], v[192:195], v[212:215], v[16:31]
	v_mfma_f32_32x32x16_bf16 v[0:15], v[196:199], v[212:215], v[0:15]
	s_waitcnt lgkmcnt(0)
	v_mfma_f32_32x32x16_bf16 v[112:127], v[216:219], v[224:227], v[112:127]
	v_mfma_f32_32x32x16_bf16 v[96:111], v[220:223], v[224:227], v[96:111]
	v_mfma_f32_32x32x16_bf16 v[80:95], v[216:219], v[228:231], v[80:95]
	v_mfma_f32_32x32x16_bf16 v[64:79], v[220:223], v[228:231], v[64:79]
	s_add_u32 s28, s28, 0x80
	s_addc_u32 s29, s29, 0
	s_add_i32 s46, s46, 0x10000
	s_add_u32 s52, s52, 0x80
	s_cmp_eq_u32 s52, 0xf80
	s_cselect_b32 s52, 0, s52
	s_xor_b32 s50, s33, 0x10000
	s_add_i32 s50, s50, 16
	s_waitcnt vmcnt(0)
	s_barrier
	v_add_u32_e32 v240, s50, v147
	v_add_u32_e32 v243, v240, v150
	v_add3_u32 v241, v240, v148, v149
	ds_read_b128 v[192:195], v243 offset:32768
	ds_read_b128 v[200:203], v241
	ds_read_b128 v[196:199], v243 offset:36864
	ds_read_b128 v[204:207], v241 offset:4096
	ds_read_b128 v[208:211], v241 offset:8192
	ds_read_b128 v[212:215], v241 offset:12288
	v_mfma_f32_32x32x16_bf16 v[48:63], v[216:219], v[232:235], v[48:63]
	v_mfma_f32_32x32x16_bf16 v[32:47], v[220:223], v[232:235], v[32:47]
	v_mfma_f32_32x32x16_bf16 v[16:31], v[216:219], v[236:239], v[16:31]
	v_mfma_f32_32x32x16_bf16 v[0:15], v[220:223], v[236:239], v[0:15]
	s_cmpk_lg_i32 s28, 0xf80
	s_cbranch_scc1 .Lgk3_loop
	v_add_u32_e32 v240, s50, v151
	v_add_u32_e32 v243, v240, v150
	v_add3_u32 v241, v240, v148, v149
	ds_read_b128 v[216:219], v243 offset:32768
	ds_read_b128 v[224:227], v241
	ds_read_b128 v[220:223], v243 offset:36864
	ds_read_b128 v[228:231], v241 offset:4096
	ds_read_b128 v[232:235], v241 offset:8192
	ds_read_b128 v[236:239], v241 offset:12288
	s_waitcnt lgkmcnt(6)
	v_mfma_f32_32x32x16_bf16 v[112:127], v[192:195], v[200:203], v[112:127]
	v_mfma_f32_32x32x16_bf16 v[96:111], v[196:199], v[200:203], v[96:111]
	v_mfma_f32_32x32x16_bf16 v[80:95], v[192:195], v[204:207], v[80:95]
	v_mfma_f32_32x32x16_bf16 v[64:79], v[196:199], v[204:207], v[64:79]
	v_mfma_f32_32x32x16_bf16 v[48:63], v[192:195], v[208:211], v[48:63]
	v_mfma_f32_32x32x16_bf16 v[32:47], v[196:199], v[208:211], v[32:47]
	v_mfma_f32_32x32x16_bf16 v[16:31], v[192:195], v[212:215], v[16:31]
	v_mfma_f32_32x32x16_bf16 v[0:15], v[196:199], v[212:215], v[0:15]
	v_add_u32_e32 v240, s50, v152
	v_add_u32_e32 v243, v240, v150
	v_add3_u32 v241, v240, v148, v149
	ds_read_b128 v[192:195], v243 offset:32768
	ds_read_b128 v[200:203], v241
	ds_read_b128 v[196:199], v243 offset:36864
	ds_read_b128 v[204:207], v241 offset:4096
	ds_read_b128 v[208:211], v241 offset:8192
	ds_read_b128 v[212:215], v241 offset:12288
	s_waitcnt lgkmcnt(6)
	v_mfma_f32_32x32x16_bf16 v[112:127], v[216:219], v[224:227], v[112:127]
	v_mfma_f32_32x32x16_bf16 v[96:111], v[220:223], v[224:227], v[96:111]
	v_mfma_f32_32x32x16_bf16 v[80:95], v[216:219], v[228:231], v[80:95]
	v_mfma_f32_32x32x16_bf16 v[64:79], v[220:223], v[228:231], v[64:79]
	v_mfma_f32_32x32x16_bf16 v[48:63], v[216:219], v[232:235], v[48:63]
	v_mfma_f32_32x32x16_bf16 v[32:47], v[220:223], v[232:235], v[32:47]
	v_mfma_f32_32x32x16_bf16 v[16:31], v[216:219], v[236:239], v[16:31]
	v_mfma_f32_32x32x16_bf16 v[0:15], v[220:223], v[236:239], v[0:15]
	v_add_u32_e32 v240, s50, v153
	v_add_u32_e32 v243, v240, v150
	v_add3_u32 v241, v240, v148, v149
	ds_read_b128 v[216:219], v243 offset:32768
	ds_read_b128 v[224:227], v241
	ds_read_b128 v[220:223], v243 offset:36864
	ds_read_b128 v[228:231], v241 offset:4096
	ds_read_b128 v[232:235], v241 offset:8192
	ds_read_b128 v[236:239], v241 offset:12288
	s_waitcnt lgkmcnt(6)
	v_mfma_f32_32x32x16_bf16 v[112:127], v[192:195], v[200:203], v[112:127]
	v_mfma_f32_32x32x16_bf16 v[96:111], v[196:199], v[200:203], v[96:111]
	v_mfma_f32_32x32x16_bf16 v[80:95], v[192:195], v[204:207], v[80:95]
	v_mfma_f32_32x32x16_bf16 v[64:79], v[196:199], v[204:207], v[64:79]
	v_mfma_f32_32x32x16_bf16 v[48:63], v[192:195], v[208:211], v[48:63]
	v_mfma_f32_32x32x16_bf16 v[32:47], v[196:199], v[208:211], v[32:47]
	v_mfma_f32_32x32x16_bf16 v[16:31], v[192:195], v[212:215], v[16:31]
	v_mfma_f32_32x32x16_bf16 v[0:15], v[196:199], v[212:215], v[0:15]
	s_waitcnt vmcnt(0) lgkmcnt(0)
	s_barrier
	v_mfma_f32_32x32x16_bf16 v[112:127], v[216:219], v[224:227], v[112:127]
	v_mfma_f32_32x32x16_bf16 v[96:111], v[220:223], v[224:227], v[96:111]
	v_mfma_f32_32x32x16_bf16 v[80:95], v[216:219], v[228:231], v[80:95]
	v_mfma_f32_32x32x16_bf16 v[64:79], v[220:223], v[228:231], v[64:79]
	v_mfma_f32_32x32x16_bf16 v[48:63], v[216:219], v[232:235], v[48:63]
	v_mfma_f32_32x32x16_bf16 v[32:47], v[220:223], v[232:235], v[32:47]
	v_mfma_f32_32x32x16_bf16 v[16:31], v[216:219], v[236:239], v[16:31]
	v_mfma_f32_32x32x16_bf16 v[0:15], v[220:223], v[236:239], v[0:15]
	s_nop 15

	.amdhsa_kernel _Z14fwd_megakernel6Params
		.amdhsa_group_segment_fixed_size 16
		.amdhsa_private_segment_fixed_size 0
		.amdhsa_kernarg_size 608
		.amdhsa_user_sgpr_count 2
		.amdhsa_user_sgpr_dispatch_ptr 0
		.amdhsa_user_sgpr_queue_ptr 0
		.amdhsa_user_sgpr_kernarg_segment_ptr 1
		.amdhsa_user_sgpr_dispatch_id 0
		.amdhsa_user_sgpr_kernarg_preload_length 0
		.amdhsa_user_sgpr_kernarg_preload_offset 0
		.amdhsa_user_sgpr_private_segment_size 0
		.amdhsa_uses_dynamic_stack 0
		.amdhsa_enable_private_segment 0
		.amdhsa_system_sgpr_workgroup_id_x 1
		.amdhsa_system_sgpr_workgroup_id_y 0
		.amdhsa_system_sgpr_workgroup_id_z 0
		.amdhsa_system_sgpr_workgroup_info 0
		.amdhsa_system_vgpr_workitem_id 2
		.amdhsa_next_free_vgpr 256
		.amdhsa_next_free_sgpr 100
		.amdhsa_accum_offset 256
		.amdhsa_reserve_vcc 1
		.amdhsa_float_round_mode_32 0
		.amdhsa_float_round_mode_16_64 0
		.amdhsa_float_denorm_mode_32 3
		.amdhsa_float_denorm_mode_16_64 3
		.amdhsa_dx10_clamp 1
		.amdhsa_ieee_mode 1
		.amdhsa_fp16_overflow 0
		.amdhsa_tg_split 0
		.amdhsa_exception_fp_ieee_invalid_op 0
		.amdhsa_exception_fp_denorm_src 0
		.amdhsa_exception_fp_ieee_div_zero 0
		.amdhsa_exception_fp_ieee_overflow 0
		.amdhsa_exception_fp_ieee_underflow 0
		.amdhsa_exception_fp_ieee_inexact 0
		.amdhsa_exception_int_div_zero 0
	.end_amdhsa_kernel

amdhsa.kernels:
  - .agpr_count:     0
    .args:
      - .offset:         0
        .size:           352
        .value_kind:     by_value
      - .offset:         352
        .size:           4
        .value_kind:     hidden_block_count_x
      - .offset:         356
        .size:           4
        .value_kind:     hidden_block_count_y
      - .offset:         360
        .size:           4
        .value_kind:     hidden_block_count_z
      - .offset:         364
        .size:           2
        .value_kind:     hidden_group_size_x
      - .offset:         366
        .size:           2
        .value_kind:     hidden_group_size_y
      - .offset:         368
        .size:           2
        .value_kind:     hidden_group_size_z
      - .offset:         370
        .size:           2
        .value_kind:     hidden_remainder_x
      - .offset:         372
        .size:           2
        .value_kind:     hidden_remainder_y
      - .offset:         374
        .size:           2
        .value_kind:     hidden_remainder_z
      - .offset:         392
        .size:           8
        .value_kind:     hidden_global_offset_x
      - .offset:         400
        .size:           8
        .value_kind:     hidden_global_offset_y
      - .offset:         408
        .size:           8
        .value_kind:     hidden_global_offset_z
      - .offset:         416
        .size:           2
        .value_kind:     hidden_grid_dims
      - .offset:         440
        .size:           8
        .value_kind:     hidden_multigrid_sync_arg
      - .offset:         472
        .size:           4
        .value_kind:     hidden_dynamic_lds_size
    .group_segment_fixed_size: 16
    .kernarg_segment_align: 8
    .kernarg_segment_size: 608
    .language:       OpenCL C
    .language_version:
      - 2
      - 0
    .max_flat_workgroup_size: 512
    .name:           _Z14fwd_megakernel6Params
    .private_segment_fixed_size: 0
    .sgpr_count:     106
    .sgpr_spill_count: 1
    .symbol:         _Z14fwd_megakernel6Params.kd
    .uniform_work_group_size: 1
    .uses_dynamic_stack: false
    .vgpr_count:     256
    .vgpr_spill_count: 0
    .wavefront_size: 64
